# barrier / flag poll loops back off 4x longer between polls (s_sleep 4): fewer uncached poll loads on the fabric while other workgroups still compute
# baseline (speedup 1.0000x reference)
; #define LAS __attribute__((address_space(3)))
; __global__ void __launch_bounds__(512, 2) mega(Params p) {
;   extern __shared__ __attribute__((aligned(16))) char shm_raw[];
;   cg::grid_group grid = cg::this_grid();
;   volatile LAS unsigned* st = (volatile LAS unsigned*)((LAS unsigned char*)shm_raw + 131072 + 3072);
;   if (threadIdx.x == 0) { st[0] = 0u; st[1] = 0u; st[2] = 0u; st[3] = 0u; }
;   __syncthreads();
;   if (p.ph_hi < 0) grid.sync();
;   const XcdBarrier xb = xcd_barrier_post((unsigned*)(p.ws + WS_BAR), st);
;   run_phase<0>(p); xcd_barrier(xb);
.LBB0_11:
	s_sleep 4
	global_load_dword v2, v1, s[6:7] offset:32 sc1
	s_waitcnt vmcnt(0)
	v_and_b32_e32 v2, 0xffff0000, v2
	v_cmp_ne_u32_e32 vcc, v2, v0
	s_or_b64 s[8:9], vcc, s[8:9]
	s_andn2_b64 exec, exec, s[8:9]
	s_cbranch_execnz .LBB0_11

; DI unsigned xb_ld(unsigned* p)              { return __hip_atomic_load(p, __ATOMIC_RELAXED, __HIP_MEMORY_SCOPE_AGENT); }
; DI void xcd_barrier_complete(unsigned* bar, unsigned x, unsigned& nloc, unsigned& nx) {
;     ...
;   for (;;) {
;     sum = 0u; cnt = 0u; mine = 0u;
; #pragma unroll
;     for (unsigned j = 0; j < 16; ++j) { const unsigned c = xb_ld(&bar[XB_XCNT(j)]); sum += c; cnt += (c > 0u) ? 1u : 0u; mine = (j == x) ? c : mine; }
;     if (sum == G) break;
;     __builtin_amdgcn_s_sleep(1);
;     if ((++sp & 255u) == 0u) { if (xb_ld(&bar[XB_TMO])) break; if (sp > XB_SPIN_CAP) { atomicAdd(&bar[XB_TMO], 1u); break; } }
;   }
.LBB0_46:
	global_load_dword v15, v16, s[6:7] sc1
	s_waitcnt lgkmcnt(0)
	global_load_dword v0, v16, s[8:9] sc1
	global_load_dword v1, v16, s[10:11] sc1
	global_load_dword v2, v16, s[12:13] sc1
	global_load_dword v3, v16, s[14:15] sc1
	global_load_dword v4, v16, s[16:17] sc1
	global_load_dword v5, v16, s[18:19] sc1
	global_load_dword v6, v16, s[20:21] sc1
	global_load_dword v7, v16, s[22:23] sc1
	global_load_dword v8, v16, s[24:25] sc1
	global_load_dword v9, v16, s[26:27] sc1
	global_load_dword v10, v16, s[28:29] sc1
	global_load_dword v11, v16, s[30:31] sc1
	global_load_dword v12, v16, s[34:35] sc1
	global_load_dword v13, v16, s[36:37] sc1
	global_load_dword v14, v16, s[38:39] sc1
	s_mov_b64 s[42:43], -1
	s_mov_b64 s[48:49], -1
	s_waitcnt vmcnt(14)
	v_add_u32_e32 v17, v0, v15
	s_waitcnt vmcnt(13)
	v_add_u32_e32 v17, v17, v1
	s_waitcnt vmcnt(12)
	v_add_u32_e32 v17, v17, v2
	s_waitcnt vmcnt(11)
	v_add_u32_e32 v17, v17, v3
	s_waitcnt vmcnt(10)
	v_add_u32_e32 v17, v17, v4
	s_waitcnt vmcnt(9)
	v_add_u32_e32 v17, v17, v5
	s_waitcnt vmcnt(8)
	v_add_u32_e32 v17, v17, v6
	s_waitcnt vmcnt(7)
	v_add_u32_e32 v17, v17, v7
	s_waitcnt vmcnt(6)
	v_add_u32_e32 v17, v17, v8
	s_waitcnt vmcnt(5)
	v_add_u32_e32 v17, v17, v9
	s_waitcnt vmcnt(4)
	v_add_u32_e32 v17, v17, v10
	s_waitcnt vmcnt(3)
	v_add_u32_e32 v17, v17, v11
	s_waitcnt vmcnt(2)
	v_add_u32_e32 v17, v17, v12
	s_waitcnt vmcnt(1)
	v_add_u32_e32 v17, v17, v13
	s_waitcnt vmcnt(0)
	v_add_u32_e32 v17, v17, v14
	v_cmp_eq_u32_e32 vcc, s3, v17
	s_cbranch_vccnz .LBB0_45
	s_and_b32 s40, s33, 0xff
	s_cmp_eq_u32 s40, 0
	s_mov_b64 s[52:53], -1
	s_sleep 4
	s_cbranch_scc0 .LBB0_50
	global_load_dword v17, v16, s[4:5] sc1
	s_waitcnt vmcnt(0)
	v_cmp_eq_u32_e32 vcc, 0, v17
	s_cbranch_vccnz .LBB0_52
	s_mov_b64 s[52:53], 0

.LBB0_64:
	s_and_b32 s20, s3, 0xff
	s_mov_b64 s[18:19], -1
	s_cmp_lg_u32 s20, 0
	s_mov_b64 s[22:23], -1
	s_sleep 4
	s_cbranch_scc1 .LBB0_67
	global_load_dword v2, v0, s[10:11] sc1
	s_waitcnt vmcnt(0)
	v_cmp_eq_u32_e32 vcc, 0, v2
	s_cbranch_vccnz .LBB0_69
	s_mov_b64 s[22:23], 0
	s_mov_b64 s[20:21], -1

.LBB0_81:
	s_and_b32 s18, s3, 0xff
	s_cmp_lg_u32 s18, 0
	s_mov_b64 s[20:21], -1
	s_sleep 4
	s_cbranch_scc1 .LBB0_84
	global_load_dword v1, v0, s[10:11] sc1
	s_waitcnt vmcnt(0)
	v_cmp_eq_u32_e32 vcc, 0, v1
	s_cbranch_vccnz .LBB0_86
	s_mov_b64 s[20:21], 0
	s_mov_b64 s[18:19], -1

; DI unsigned xb_ld(unsigned* p)              { return __hip_atomic_load(p, __ATOMIC_RELAXED, __HIP_MEMORY_SCOPE_AGENT); }
; DI void xcd_barrier_complete(unsigned* bar, unsigned x, unsigned& nloc, unsigned& nx) {
;     ...
;   for (;;) {
;     sum = 0u; cnt = 0u; mine = 0u;
; #pragma unroll
;     for (unsigned j = 0; j < 16; ++j) { const unsigned c = xb_ld(&bar[XB_XCNT(j)]); sum += c; cnt += (c > 0u) ? 1u : 0u; mine = (j == x) ? c : mine; }
;     if (sum == G) break;
;     __builtin_amdgcn_s_sleep(1);
;     if ((++sp & 255u) == 0u) { if (xb_ld(&bar[XB_TMO])) break; if (sp > XB_SPIN_CAP) { atomicAdd(&bar[XB_TMO], 1u); break; } }
;   }
.LBB0_903:
	global_load_dword v15, v16, s[6:7] sc1
	s_waitcnt lgkmcnt(0)
	global_load_dword v0, v16, s[8:9] sc1
	global_load_dword v1, v16, s[10:11] sc1
	global_load_dword v2, v16, s[12:13] sc1
	global_load_dword v3, v16, s[14:15] sc1
	global_load_dword v4, v16, s[16:17] sc1
	global_load_dword v5, v16, s[18:19] sc1
	global_load_dword v6, v16, s[20:21] sc1
	global_load_dword v7, v16, s[22:23] sc1
	global_load_dword v8, v16, s[24:25] sc1
	global_load_dword v9, v16, s[26:27] sc1
	global_load_dword v10, v16, s[28:29] sc1
	global_load_dword v11, v16, s[30:31] sc1
	global_load_dword v12, v16, s[34:35] sc1
	global_load_dword v13, v16, s[36:37] sc1
	global_load_dword v14, v16, s[38:39] sc1
	s_mov_b64 s[42:43], -1
	s_mov_b64 s[64:65], -1
	s_waitcnt vmcnt(14)
	v_add_u32_e32 v17, v0, v15
	s_waitcnt vmcnt(13)
	v_add_u32_e32 v17, v17, v1
	s_waitcnt vmcnt(12)
	v_add_u32_e32 v17, v17, v2
	s_waitcnt vmcnt(11)
	v_add_u32_e32 v17, v17, v3
	s_waitcnt vmcnt(10)
	v_add_u32_e32 v17, v17, v4
	s_waitcnt vmcnt(9)
	v_add_u32_e32 v17, v17, v5
	s_waitcnt vmcnt(8)
	v_add_u32_e32 v17, v17, v6
	s_waitcnt vmcnt(7)
	v_add_u32_e32 v17, v17, v7
	s_waitcnt vmcnt(6)
	v_add_u32_e32 v17, v17, v8
	s_waitcnt vmcnt(5)
	v_add_u32_e32 v17, v17, v9
	s_waitcnt vmcnt(4)
	v_add_u32_e32 v17, v17, v10
	s_waitcnt vmcnt(3)
	v_add_u32_e32 v17, v17, v11
	s_waitcnt vmcnt(2)
	v_add_u32_e32 v17, v17, v12
	s_waitcnt vmcnt(1)
	v_add_u32_e32 v17, v17, v13
	s_waitcnt vmcnt(0)
	v_add_u32_e32 v17, v17, v14
	v_cmp_eq_u32_e32 vcc, s3, v17
	s_cbranch_vccnz .LBB0_902
	s_and_b32 s40, s33, 0xff
	s_cmp_eq_u32 s40, 0
	s_mov_b64 s[66:67], -1
	s_sleep 4
	s_cbranch_scc0 .LBB0_907
	global_load_dword v17, v16, s[4:5] sc1
	s_waitcnt vmcnt(0)
	v_cmp_eq_u32_e32 vcc, 0, v17
	s_cbranch_vccnz .LBB0_909
	s_mov_b64 s[66:67], 0

; DI void phase_mixer(const Params& p) {
;     ...
;   for (;;) {
;     __syncthreads();
;     if (threadIdx.x == 0) *sItem = (int)atomicAdd(ctr, 1u);
;     __syncthreads();
;     const int it = *sItem;
;     if (it >= 48 + 2048) break;
;     if (it < 48) hgrn_item(p, it); else attn_item(p, it - 48);
.Lcq_spin:
	global_load_dword v1, v0, s[82:83] offset:64 sc1
	s_waitcnt vmcnt(0)
	v_readfirstlane_b32 s3, v1
	s_cmp_ge_u32 s3, 48
	s_cbranch_scc1 .Lcq_ok
	s_sleep 4
	s_branch .Lcq_spin

; DI unsigned xb_ld(unsigned* p)              { return __hip_atomic_load(p, __ATOMIC_RELAXED, __HIP_MEMORY_SCOPE_AGENT); }
; DI void xcd_barrier_complete(unsigned* bar, unsigned x, unsigned& nloc, unsigned& nx) {
;     ...
;   for (;;) {
;     sum = 0u; cnt = 0u; mine = 0u;
; #pragma unroll
;     for (unsigned j = 0; j < 16; ++j) { const unsigned c = xb_ld(&bar[XB_XCNT(j)]); sum += c; cnt += (c > 0u) ? 1u : 0u; mine = (j == x) ? c : mine; }
;     if (sum == G) break;
;     __builtin_amdgcn_s_sleep(1);
;     if ((++sp & 255u) == 0u) { if (xb_ld(&bar[XB_TMO])) break; if (sp > XB_SPIN_CAP) { atomicAdd(&bar[XB_TMO], 1u); break; } }
;   }
.LBB0_1068:
	global_load_dword v15, v16, s[6:7] sc1
	s_waitcnt lgkmcnt(0)
	global_load_dword v0, v16, s[8:9] sc1
	global_load_dword v1, v16, s[10:11] sc1
	global_load_dword v2, v16, s[12:13] sc1
	global_load_dword v3, v16, s[14:15] sc1
	global_load_dword v4, v16, s[16:17] sc1
	global_load_dword v5, v16, s[18:19] sc1
	global_load_dword v6, v16, s[20:21] sc1
	global_load_dword v7, v16, s[22:23] sc1
	global_load_dword v8, v16, s[24:25] sc1
	global_load_dword v9, v16, s[26:27] sc1
	global_load_dword v10, v16, s[28:29] sc1
	global_load_dword v11, v16, s[30:31] sc1
	global_load_dword v12, v16, s[34:35] sc1
	global_load_dword v13, v16, s[36:37] sc1
	global_load_dword v14, v16, s[38:39] sc1
	s_mov_b64 s[42:43], -1
	s_mov_b64 s[46:47], -1
	s_waitcnt vmcnt(14)
	v_add_u32_e32 v17, v0, v15
	s_waitcnt vmcnt(13)
	v_add_u32_e32 v17, v17, v1
	s_waitcnt vmcnt(12)
	v_add_u32_e32 v17, v17, v2
	s_waitcnt vmcnt(11)
	v_add_u32_e32 v17, v17, v3
	s_waitcnt vmcnt(10)
	v_add_u32_e32 v17, v17, v4
	s_waitcnt vmcnt(9)
	v_add_u32_e32 v17, v17, v5
	s_waitcnt vmcnt(8)
	v_add_u32_e32 v17, v17, v6
	s_waitcnt vmcnt(7)
	v_add_u32_e32 v17, v17, v7
	s_waitcnt vmcnt(6)
	v_add_u32_e32 v17, v17, v8
	s_waitcnt vmcnt(5)
	v_add_u32_e32 v17, v17, v9
	s_waitcnt vmcnt(4)
	v_add_u32_e32 v17, v17, v10
	s_waitcnt vmcnt(3)
	v_add_u32_e32 v17, v17, v11
	s_waitcnt vmcnt(2)
	v_add_u32_e32 v17, v17, v12
	s_waitcnt vmcnt(1)
	v_add_u32_e32 v17, v17, v13
	s_waitcnt vmcnt(0)
	v_add_u32_e32 v17, v17, v14
	v_cmp_eq_u32_e32 vcc, s3, v17
	s_cbranch_vccnz .LBB0_1067
	s_and_b32 s40, s33, 0xff
	s_cmp_eq_u32 s40, 0
	s_mov_b64 s[64:65], -1
	s_sleep 4
	s_cbranch_scc0 .LBB0_1072
	global_load_dword v17, v16, s[4:5] sc1
	s_waitcnt vmcnt(0)
	v_cmp_eq_u32_e32 vcc, 0, v17
	s_cbranch_vccnz .LBB0_1074
	s_mov_b64 s[64:65], 0

; DI unsigned xb_ld(unsigned* p)              { return __hip_atomic_load(p, __ATOMIC_RELAXED, __HIP_MEMORY_SCOPE_AGENT); }
; DI void xcd_barrier_complete(unsigned* bar, unsigned x, unsigned& nloc, unsigned& nx) {
;     ...
;   for (;;) {
;     sum = 0u; cnt = 0u; mine = 0u;
; #pragma unroll
;     for (unsigned j = 0; j < 16; ++j) { const unsigned c = xb_ld(&bar[XB_XCNT(j)]); sum += c; cnt += (c > 0u) ? 1u : 0u; mine = (j == x) ? c : mine; }
;     if (sum == G) break;
;     __builtin_amdgcn_s_sleep(1);
;     if ((++sp & 255u) == 0u) { if (xb_ld(&bar[XB_TMO])) break; if (sp > XB_SPIN_CAP) { atomicAdd(&bar[XB_TMO], 1u); break; } }
;   }
.LBB0_1146:
	global_load_dword v15, v16, s[12:13] sc1
	s_waitcnt lgkmcnt(0)
	global_load_dword v0, v16, s[14:15] sc1
	global_load_dword v1, v16, s[16:17] sc1
	global_load_dword v2, v16, s[18:19] sc1
	global_load_dword v3, v16, s[20:21] sc1
	global_load_dword v4, v16, s[22:23] sc1
	global_load_dword v5, v16, s[24:25] sc1
	global_load_dword v6, v16, s[26:27] sc1
	global_load_dword v7, v16, s[28:29] sc1
	global_load_dword v8, v16, s[30:31] sc1
	global_load_dword v9, v16, s[34:35] sc1
	global_load_dword v10, v16, s[36:37] sc1
	global_load_dword v11, v16, s[38:39] sc1
	global_load_dword v12, v16, s[42:43] sc1
	global_load_dword v13, v16, s[46:47] sc1
	global_load_dword v14, v16, s[50:51] sc1
	s_mov_b64 s[60:61], -1
	s_mov_b64 s[62:63], -1
	s_waitcnt vmcnt(14)
	v_add_u32_e32 v17, v0, v15
	s_waitcnt vmcnt(13)
	v_add_u32_e32 v17, v17, v1
	s_waitcnt vmcnt(12)
	v_add_u32_e32 v17, v17, v2
	s_waitcnt vmcnt(11)
	v_add_u32_e32 v17, v17, v3
	s_waitcnt vmcnt(10)
	v_add_u32_e32 v17, v17, v4
	s_waitcnt vmcnt(9)
	v_add_u32_e32 v17, v17, v5
	s_waitcnt vmcnt(8)
	v_add_u32_e32 v17, v17, v6
	s_waitcnt vmcnt(7)
	v_add_u32_e32 v17, v17, v7
	s_waitcnt vmcnt(6)
	v_add_u32_e32 v17, v17, v8
	s_waitcnt vmcnt(5)
	v_add_u32_e32 v17, v17, v9
	s_waitcnt vmcnt(4)
	v_add_u32_e32 v17, v17, v10
	s_waitcnt vmcnt(3)
	v_add_u32_e32 v17, v17, v11
	s_waitcnt vmcnt(2)
	v_add_u32_e32 v17, v17, v12
	s_waitcnt vmcnt(1)
	v_add_u32_e32 v17, v17, v13
	s_waitcnt vmcnt(0)
	v_add_u32_e32 v17, v17, v14
	v_cmp_eq_u32_e32 vcc, s3, v17
	s_cbranch_vccnz .LBB0_1145
	s_and_b32 s7, s5, 0xff
	s_cmp_eq_u32 s7, 0
	s_mov_b64 s[64:65], -1
	s_sleep 4
	s_cbranch_scc0 .LBB0_1150
	global_load_dword v17, v16, s[10:11] sc1
	s_waitcnt vmcnt(0)
	v_cmp_eq_u32_e32 vcc, 0, v17
	s_cbranch_vccnz .LBB0_1152
	s_mov_b64 s[64:65], 0

.LBB0_1164:
	s_and_b32 s5, s3, 0xff
	s_mov_b64 s[24:25], -1
	s_cmp_lg_u32 s5, 0
	s_mov_b64 s[28:29], -1
	s_sleep 4
	s_cbranch_scc1 .LBB0_1167
	global_load_dword v2, v0, s[16:17] sc1
	s_waitcnt vmcnt(0)
	v_cmp_eq_u32_e32 vcc, 0, v2
	s_cbranch_vccnz .LBB0_1169
	s_mov_b64 s[28:29], 0
	s_mov_b64 s[26:27], -1

.LBB0_1181:
	s_and_b32 s5, s3, 0xff
	s_cmp_lg_u32 s5, 0
	s_mov_b64 s[26:27], -1
	s_sleep 4
	s_cbranch_scc1 .LBB0_1184
	global_load_dword v1, v0, s[16:17] sc1
	s_waitcnt vmcnt(0)
	v_cmp_eq_u32_e32 vcc, 0, v1
	s_cbranch_vccnz .LBB0_1186
	s_mov_b64 s[26:27], 0
	s_mov_b64 s[24:25], -1

; DI unsigned xb_ld(unsigned* p)              { return __hip_atomic_load(p, __ATOMIC_RELAXED, __HIP_MEMORY_SCOPE_AGENT); }
; DI void xcd_barrier_complete(unsigned* bar, unsigned x, unsigned& nloc, unsigned& nx) {
;     ...
;   for (;;) {
;     sum = 0u; cnt = 0u; mine = 0u;
; #pragma unroll
;     for (unsigned j = 0; j < 16; ++j) { const unsigned c = xb_ld(&bar[XB_XCNT(j)]); sum += c; cnt += (c > 0u) ? 1u : 0u; mine = (j == x) ? c : mine; }
;     if (sum == G) break;
;     __builtin_amdgcn_s_sleep(1);
;     if ((++sp & 255u) == 0u) { if (xb_ld(&bar[XB_TMO])) break; if (sp > XB_SPIN_CAP) { atomicAdd(&bar[XB_TMO], 1u); break; } }
;   }
.LBB0_1210:
	global_load_dword v15, v16, s[12:13] sc1
	s_waitcnt lgkmcnt(0)
	global_load_dword v0, v16, s[14:15] sc1
	global_load_dword v1, v16, s[16:17] sc1
	global_load_dword v2, v16, s[18:19] sc1
	global_load_dword v3, v16, s[20:21] sc1
	global_load_dword v4, v16, s[22:23] sc1
	global_load_dword v5, v16, s[24:25] sc1
	global_load_dword v6, v16, s[26:27] sc1
	global_load_dword v7, v16, s[28:29] sc1
	global_load_dword v8, v16, s[30:31] sc1
	global_load_dword v9, v16, s[34:35] sc1
	global_load_dword v10, v16, s[36:37] sc1
	global_load_dword v11, v16, s[38:39] sc1
	global_load_dword v12, v16, s[40:41] sc1
	global_load_dword v13, v16, s[42:43] sc1
	global_load_dword v14, v16, s[44:45] sc1
	s_mov_b64 s[46:47], -1
	s_mov_b64 s[50:51], -1
	s_waitcnt vmcnt(14)
	v_add_u32_e32 v17, v0, v15
	s_waitcnt vmcnt(13)
	v_add_u32_e32 v17, v17, v1
	s_waitcnt vmcnt(12)
	v_add_u32_e32 v17, v17, v2
	s_waitcnt vmcnt(11)
	v_add_u32_e32 v17, v17, v3
	s_waitcnt vmcnt(10)
	v_add_u32_e32 v17, v17, v4
	s_waitcnt vmcnt(9)
	v_add_u32_e32 v17, v17, v5
	s_waitcnt vmcnt(8)
	v_add_u32_e32 v17, v17, v6
	s_waitcnt vmcnt(7)
	v_add_u32_e32 v17, v17, v7
	s_waitcnt vmcnt(6)
	v_add_u32_e32 v17, v17, v8
	s_waitcnt vmcnt(5)
	v_add_u32_e32 v17, v17, v9
	s_waitcnt vmcnt(4)
	v_add_u32_e32 v17, v17, v10
	s_waitcnt vmcnt(3)
	v_add_u32_e32 v17, v17, v11
	s_waitcnt vmcnt(2)
	v_add_u32_e32 v17, v17, v12
	s_waitcnt vmcnt(1)
	v_add_u32_e32 v17, v17, v13
	s_waitcnt vmcnt(0)
	v_add_u32_e32 v17, v17, v14
	v_cmp_eq_u32_e32 vcc, s3, v17
	s_cbranch_vccnz .LBB0_1209
	s_and_b32 s7, s5, 0xff
	s_cmp_eq_u32 s7, 0
	s_mov_b64 s[60:61], -1
	s_sleep 4
	s_cbranch_scc0 .LBB0_1214
	global_load_dword v17, v16, s[10:11] sc1
	s_waitcnt vmcnt(0)
	v_cmp_eq_u32_e32 vcc, 0, v17
	s_cbranch_vccnz .LBB0_1216
	s_mov_b64 s[60:61], 0
